# top-16 threshold search (prompt unit rows and sample item): 31-step loop fully unrolled, 5 instructions per bit, scalar compare of the ballot count
# speedup vs baseline: 1.0091x; 1.0060x over previous
; __device__ __forceinline__ void attn_prompt_unit(const AttnArgs& a, int n, int g, int qt, LAS unsigned char* lds, int tid) {
;     ...
;                     unsigned thr1 = 0u;
; #pragma unroll 1
;     ...
;                     const unsigned long long gt = __ballot(key1 > thr1); unsigned long long eq = __ballot(key1 == thr1);
;                     int need = 16 - __popcll(gt); sel = gt;
.LBB0_2560:
	s_or_b32 s15, s20, 0x40000000
	v_cmp_le_u32_e32 vcc, s15, v2
	s_bcnt1_i32_b64 s54, vcc
	s_cmp_gt_u32 s54, 15
	s_cselect_b32 s20, s15, s20
	s_or_b32 s15, s20, 0x20000000
	v_cmp_le_u32_e32 vcc, s15, v2
	s_bcnt1_i32_b64 s54, vcc
	s_cmp_gt_u32 s54, 15
	s_cselect_b32 s20, s15, s20
	s_or_b32 s15, s20, 0x10000000
	v_cmp_le_u32_e32 vcc, s15, v2
	s_bcnt1_i32_b64 s54, vcc
	s_cmp_gt_u32 s54, 15
	s_cselect_b32 s20, s15, s20
	s_or_b32 s15, s20, 0x8000000
	v_cmp_le_u32_e32 vcc, s15, v2
	s_bcnt1_i32_b64 s54, vcc
	s_cmp_gt_u32 s54, 15
	s_cselect_b32 s20, s15, s20
	s_or_b32 s15, s20, 0x4000000
	v_cmp_le_u32_e32 vcc, s15, v2
	s_bcnt1_i32_b64 s54, vcc
	s_cmp_gt_u32 s54, 15
	s_cselect_b32 s20, s15, s20
	s_or_b32 s15, s20, 0x2000000
	v_cmp_le_u32_e32 vcc, s15, v2
	s_bcnt1_i32_b64 s54, vcc
	s_cmp_gt_u32 s54, 15
	s_cselect_b32 s20, s15, s20
	s_or_b32 s15, s20, 0x1000000
	v_cmp_le_u32_e32 vcc, s15, v2
	s_bcnt1_i32_b64 s54, vcc
	s_cmp_gt_u32 s54, 15
	s_cselect_b32 s20, s15, s20
	s_or_b32 s15, s20, 0x800000
	v_cmp_le_u32_e32 vcc, s15, v2
	s_bcnt1_i32_b64 s54, vcc
	s_cmp_gt_u32 s54, 15
	s_cselect_b32 s20, s15, s20
	s_or_b32 s15, s20, 0x400000
	v_cmp_le_u32_e32 vcc, s15, v2
	s_bcnt1_i32_b64 s54, vcc
	s_cmp_gt_u32 s54, 15
	s_cselect_b32 s20, s15, s20
	s_or_b32 s15, s20, 0x200000
	v_cmp_le_u32_e32 vcc, s15, v2
	s_bcnt1_i32_b64 s54, vcc
	s_cmp_gt_u32 s54, 15
	s_cselect_b32 s20, s15, s20
	s_or_b32 s15, s20, 0x100000
	v_cmp_le_u32_e32 vcc, s15, v2
	s_bcnt1_i32_b64 s54, vcc
	s_cmp_gt_u32 s54, 15
	s_cselect_b32 s20, s15, s20
	s_or_b32 s15, s20, 0x80000
	v_cmp_le_u32_e32 vcc, s15, v2
	s_bcnt1_i32_b64 s54, vcc
	s_cmp_gt_u32 s54, 15
	s_cselect_b32 s20, s15, s20
	s_or_b32 s15, s20, 0x40000
	v_cmp_le_u32_e32 vcc, s15, v2
	s_bcnt1_i32_b64 s54, vcc
	s_cmp_gt_u32 s54, 15
	s_cselect_b32 s20, s15, s20
	s_or_b32 s15, s20, 0x20000
	v_cmp_le_u32_e32 vcc, s15, v2
	s_bcnt1_i32_b64 s54, vcc
	s_cmp_gt_u32 s54, 15
	s_cselect_b32 s20, s15, s20
	s_or_b32 s15, s20, 0x10000
	v_cmp_le_u32_e32 vcc, s15, v2
	s_bcnt1_i32_b64 s54, vcc
	s_cmp_gt_u32 s54, 15
	s_cselect_b32 s20, s15, s20
	s_or_b32 s15, s20, 0x8000
	v_cmp_le_u32_e32 vcc, s15, v2
	s_bcnt1_i32_b64 s54, vcc
	s_cmp_gt_u32 s54, 15
	s_cselect_b32 s20, s15, s20
	s_or_b32 s15, s20, 0x4000
	v_cmp_le_u32_e32 vcc, s15, v2
	s_bcnt1_i32_b64 s54, vcc
	s_cmp_gt_u32 s54, 15
	s_cselect_b32 s20, s15, s20
	s_or_b32 s15, s20, 0x2000
	v_cmp_le_u32_e32 vcc, s15, v2
	s_bcnt1_i32_b64 s54, vcc
	s_cmp_gt_u32 s54, 15
	s_cselect_b32 s20, s15, s20
	s_or_b32 s15, s20, 0x1000
	v_cmp_le_u32_e32 vcc, s15, v2
	s_bcnt1_i32_b64 s54, vcc
	s_cmp_gt_u32 s54, 15
	s_cselect_b32 s20, s15, s20
	s_or_b32 s15, s20, 0x800
	v_cmp_le_u32_e32 vcc, s15, v2
	s_bcnt1_i32_b64 s54, vcc
	s_cmp_gt_u32 s54, 15
	s_cselect_b32 s20, s15, s20
	s_or_b32 s15, s20, 0x400
	v_cmp_le_u32_e32 vcc, s15, v2
	s_bcnt1_i32_b64 s54, vcc
	s_cmp_gt_u32 s54, 15
	s_cselect_b32 s20, s15, s20
	s_or_b32 s15, s20, 0x200
	v_cmp_le_u32_e32 vcc, s15, v2
	s_bcnt1_i32_b64 s54, vcc
	s_cmp_gt_u32 s54, 15
	s_cselect_b32 s20, s15, s20
	s_or_b32 s15, s20, 0x100
	v_cmp_le_u32_e32 vcc, s15, v2
	s_bcnt1_i32_b64 s54, vcc
	s_cmp_gt_u32 s54, 15
	s_cselect_b32 s20, s15, s20
	s_or_b32 s15, s20, 0x80
	v_cmp_le_u32_e32 vcc, s15, v2
	s_bcnt1_i32_b64 s54, vcc
	s_cmp_gt_u32 s54, 15
	s_cselect_b32 s20, s15, s20
	s_or_b32 s15, s20, 64
	v_cmp_le_u32_e32 vcc, s15, v2
	s_bcnt1_i32_b64 s54, vcc
	s_cmp_gt_u32 s54, 15
	s_cselect_b32 s20, s15, s20
	s_or_b32 s15, s20, 32
	v_cmp_le_u32_e32 vcc, s15, v2
	s_bcnt1_i32_b64 s54, vcc
	s_cmp_gt_u32 s54, 15
	s_cselect_b32 s20, s15, s20
	s_or_b32 s15, s20, 16
	v_cmp_le_u32_e32 vcc, s15, v2
	s_bcnt1_i32_b64 s54, vcc
	s_cmp_gt_u32 s54, 15
	s_cselect_b32 s20, s15, s20
	s_or_b32 s15, s20, 8
	v_cmp_le_u32_e32 vcc, s15, v2
	s_bcnt1_i32_b64 s54, vcc
	s_cmp_gt_u32 s54, 15
	s_cselect_b32 s20, s15, s20
	s_or_b32 s15, s20, 4
	v_cmp_le_u32_e32 vcc, s15, v2
	s_bcnt1_i32_b64 s54, vcc
	s_cmp_gt_u32 s54, 15
	s_cselect_b32 s20, s15, s20
	s_or_b32 s15, s20, 2
	v_cmp_le_u32_e32 vcc, s15, v2
	s_bcnt1_i32_b64 s54, vcc
	s_cmp_gt_u32 s54, 15
	s_cselect_b32 s20, s15, s20
	s_or_b32 s15, s20, 1
	v_cmp_le_u32_e32 vcc, s15, v2
	s_bcnt1_i32_b64 s54, vcc
	s_cmp_gt_u32 s54, 15
	s_cselect_b32 s20, s15, s20
	v_cmp_lt_u32_e64 s[14:15], s20, v2
	v_cmp_eq_u32_e64 s[20:21], s20, v2
	s_bcnt1_i32_b64 s54, s[14:15]
	s_cmp_eq_u64 s[20:21], 0
	v_cmp_gt_u64_e64 s[22:23], s[54:55], 15
	s_cselect_b64 s[24:25], -1, 0
	s_or_b64 s[22:23], s[22:23], s[24:25]
	s_and_b64 vcc, exec, s[22:23]
	s_cbranch_vccnz .LBB0_2564
	s_sub_i32 s22, 16, s54

; __device__ __forceinline__ void attn_sample_item(const SmpArgs& a, int b, int g, LAS unsigned char* lds, int tid) {
;     ...
;         const unsigned key = valid ? __float_as_uint(s + (forced ? 1e4f : 0.f)) : 0u;
;         unsigned thr = 0u;
; #pragma unroll 1
;     ...
;         const unsigned long long gt = __ballot(key > thr); unsigned long long eq = __ballot(key == thr);
;         int need = 16 - __popcll(gt); unsigned long long sel = gt;
.LBB0_2800:
	s_or_b32 s15, s16, 0x40000000
	v_cmp_le_u32_e32 vcc, s15, v0
	s_bcnt1_i32_b64 s54, vcc
	s_cmp_gt_u32 s54, 15
	s_cselect_b32 s16, s15, s16
	s_or_b32 s15, s16, 0x20000000
	v_cmp_le_u32_e32 vcc, s15, v0
	s_bcnt1_i32_b64 s54, vcc
	s_cmp_gt_u32 s54, 15
	s_cselect_b32 s16, s15, s16
	s_or_b32 s15, s16, 0x10000000
	v_cmp_le_u32_e32 vcc, s15, v0
	s_bcnt1_i32_b64 s54, vcc
	s_cmp_gt_u32 s54, 15
	s_cselect_b32 s16, s15, s16
	s_or_b32 s15, s16, 0x8000000
	v_cmp_le_u32_e32 vcc, s15, v0
	s_bcnt1_i32_b64 s54, vcc
	s_cmp_gt_u32 s54, 15
	s_cselect_b32 s16, s15, s16
	s_or_b32 s15, s16, 0x4000000
	v_cmp_le_u32_e32 vcc, s15, v0
	s_bcnt1_i32_b64 s54, vcc
	s_cmp_gt_u32 s54, 15
	s_cselect_b32 s16, s15, s16
	s_or_b32 s15, s16, 0x2000000
	v_cmp_le_u32_e32 vcc, s15, v0
	s_bcnt1_i32_b64 s54, vcc
	s_cmp_gt_u32 s54, 15
	s_cselect_b32 s16, s15, s16
	s_or_b32 s15, s16, 0x1000000
	v_cmp_le_u32_e32 vcc, s15, v0
	s_bcnt1_i32_b64 s54, vcc
	s_cmp_gt_u32 s54, 15
	s_cselect_b32 s16, s15, s16
	s_or_b32 s15, s16, 0x800000
	v_cmp_le_u32_e32 vcc, s15, v0
	s_bcnt1_i32_b64 s54, vcc
	s_cmp_gt_u32 s54, 15
	s_cselect_b32 s16, s15, s16
	s_or_b32 s15, s16, 0x400000
	v_cmp_le_u32_e32 vcc, s15, v0
	s_bcnt1_i32_b64 s54, vcc
	s_cmp_gt_u32 s54, 15
	s_cselect_b32 s16, s15, s16
	s_or_b32 s15, s16, 0x200000
	v_cmp_le_u32_e32 vcc, s15, v0
	s_bcnt1_i32_b64 s54, vcc
	s_cmp_gt_u32 s54, 15
	s_cselect_b32 s16, s15, s16
	s_or_b32 s15, s16, 0x100000
	v_cmp_le_u32_e32 vcc, s15, v0
	s_bcnt1_i32_b64 s54, vcc
	s_cmp_gt_u32 s54, 15
	s_cselect_b32 s16, s15, s16
	s_or_b32 s15, s16, 0x80000
	v_cmp_le_u32_e32 vcc, s15, v0
	s_bcnt1_i32_b64 s54, vcc
	s_cmp_gt_u32 s54, 15
	s_cselect_b32 s16, s15, s16
	s_or_b32 s15, s16, 0x40000
	v_cmp_le_u32_e32 vcc, s15, v0
	s_bcnt1_i32_b64 s54, vcc
	s_cmp_gt_u32 s54, 15
	s_cselect_b32 s16, s15, s16
	s_or_b32 s15, s16, 0x20000
	v_cmp_le_u32_e32 vcc, s15, v0
	s_bcnt1_i32_b64 s54, vcc
	s_cmp_gt_u32 s54, 15
	s_cselect_b32 s16, s15, s16
	s_or_b32 s15, s16, 0x10000
	v_cmp_le_u32_e32 vcc, s15, v0
	s_bcnt1_i32_b64 s54, vcc
	s_cmp_gt_u32 s54, 15
	s_cselect_b32 s16, s15, s16
	s_or_b32 s15, s16, 0x8000
	v_cmp_le_u32_e32 vcc, s15, v0
	s_bcnt1_i32_b64 s54, vcc
	s_cmp_gt_u32 s54, 15
	s_cselect_b32 s16, s15, s16
	s_or_b32 s15, s16, 0x4000
	v_cmp_le_u32_e32 vcc, s15, v0
	s_bcnt1_i32_b64 s54, vcc
	s_cmp_gt_u32 s54, 15
	s_cselect_b32 s16, s15, s16
	s_or_b32 s15, s16, 0x2000
	v_cmp_le_u32_e32 vcc, s15, v0
	s_bcnt1_i32_b64 s54, vcc
	s_cmp_gt_u32 s54, 15
	s_cselect_b32 s16, s15, s16
	s_or_b32 s15, s16, 0x1000
	v_cmp_le_u32_e32 vcc, s15, v0
	s_bcnt1_i32_b64 s54, vcc
	s_cmp_gt_u32 s54, 15
	s_cselect_b32 s16, s15, s16
	s_or_b32 s15, s16, 0x800
	v_cmp_le_u32_e32 vcc, s15, v0
	s_bcnt1_i32_b64 s54, vcc
	s_cmp_gt_u32 s54, 15
	s_cselect_b32 s16, s15, s16
	s_or_b32 s15, s16, 0x400
	v_cmp_le_u32_e32 vcc, s15, v0
	s_bcnt1_i32_b64 s54, vcc
	s_cmp_gt_u32 s54, 15
	s_cselect_b32 s16, s15, s16
	s_or_b32 s15, s16, 0x200
	v_cmp_le_u32_e32 vcc, s15, v0
	s_bcnt1_i32_b64 s54, vcc
	s_cmp_gt_u32 s54, 15
	s_cselect_b32 s16, s15, s16
	s_or_b32 s15, s16, 0x100
	v_cmp_le_u32_e32 vcc, s15, v0
	s_bcnt1_i32_b64 s54, vcc
	s_cmp_gt_u32 s54, 15
	s_cselect_b32 s16, s15, s16
	s_or_b32 s15, s16, 0x80
	v_cmp_le_u32_e32 vcc, s15, v0
	s_bcnt1_i32_b64 s54, vcc
	s_cmp_gt_u32 s54, 15
	s_cselect_b32 s16, s15, s16
	s_or_b32 s15, s16, 64
	v_cmp_le_u32_e32 vcc, s15, v0
	s_bcnt1_i32_b64 s54, vcc
	s_cmp_gt_u32 s54, 15
	s_cselect_b32 s16, s15, s16
	s_or_b32 s15, s16, 32
	v_cmp_le_u32_e32 vcc, s15, v0
	s_bcnt1_i32_b64 s54, vcc
	s_cmp_gt_u32 s54, 15
	s_cselect_b32 s16, s15, s16
	s_or_b32 s15, s16, 16
	v_cmp_le_u32_e32 vcc, s15, v0
	s_bcnt1_i32_b64 s54, vcc
	s_cmp_gt_u32 s54, 15
	s_cselect_b32 s16, s15, s16
	s_or_b32 s15, s16, 8
	v_cmp_le_u32_e32 vcc, s15, v0
	s_bcnt1_i32_b64 s54, vcc
	s_cmp_gt_u32 s54, 15
	s_cselect_b32 s16, s15, s16
	s_or_b32 s15, s16, 4
	v_cmp_le_u32_e32 vcc, s15, v0
	s_bcnt1_i32_b64 s54, vcc
	s_cmp_gt_u32 s54, 15
	s_cselect_b32 s16, s15, s16
	s_or_b32 s15, s16, 2
	v_cmp_le_u32_e32 vcc, s15, v0
	s_bcnt1_i32_b64 s54, vcc
	s_cmp_gt_u32 s54, 15
	s_cselect_b32 s16, s15, s16
	s_or_b32 s15, s16, 1
	v_cmp_le_u32_e32 vcc, s15, v0
	s_bcnt1_i32_b64 s54, vcc
	s_cmp_gt_u32 s54, 15
	s_cselect_b32 s16, s15, s16
	v_cmp_lt_u32_e64 s[14:15], s16, v0
	v_cmp_eq_u32_e64 s[16:17], s16, v0
	s_bcnt1_i32_b64 s54, s[14:15]
	s_cmp_eq_u64 s[16:17], 0
	v_cmp_gt_u64_e64 s[20:21], s[54:55], 15
	s_cselect_b64 s[22:23], -1, 0
	s_or_b64 s[20:21], s[20:21], s[22:23]
	s_and_b64 vcc, exec, s[20:21]
	s_cbranch_vccnz .LBB0_2804
	s_sub_i32 s19, 16, s54
